# baseline (speedup 1.0000x reference)
; __device__ __forceinline__ f32x4 mfma16(bf16x8 a, bf16x8 b, f32x4 c) { return __builtin_amdgcn_mfma_f32_16x16x32_bf16(a, b, c, 0, 0, 0); }
; __device__ __forceinline__ void qk_tiles(f32x4 (&s)[8], const bf16_t* Ks, const bf16x8 (&qf)[4], int fr, int g, int tlo, int thi) {
;   __builtin_amdgcn_s_setprio(1);
; #pragma unroll
;   for (int T = 0; T < 8; ++T) {
;     s[T] = (f32x4){0.f, 0.f, 0.f, 0.f};
;     if (T >= tlo && T <= thi) {
; #pragma unroll
;       for (int kc = 0; kc < 4; ++kc) {
;         bf16x8 a = *(const bf16x8*)(Ks + (T * 16 + fr) * LROW + kc * 32 + g * 8);
;         s[T] = mfma16(a, qf[kc], s[T]);
;       }
;     }
;   }
;   __builtin_amdgcn_s_setprio(0);
; }
; __device__ __forceinline__ void sb_item(KParams p, int tb, int hd) {
;     ...
;   for (int j = i; j >= 0; --j) {
;     __syncthreads();
;     tile_st(kreg, Ks, tid); tile_st(vreg, Vts, tid);
;     __syncthreads();
;     {
;       const int ktok0 = (b * 64 + max(j - 1, 0)) * 128;
;       kreg = tile_ld(kbase + (size_t)ktok0 * NPROJ, NPROJ, tid);
;       vreg = tile_ld(vbase + ktok0, T_TOK, tid);
;     }
;     const bool wave_live = __any(carry >= -160.f) != 0;
;     const int thi = wave_live ? ((j == i) ? rt : 7) : -1;
;     if (thi >= 0) {
;       f32x4 s[8];
;       qk_tiles(s, Ks, qf, fr, g, 0, thi);
.LBB0_284:
	s_add_i32 s10, s13, 1
	s_cmp_lt_i32 s10, 0
	s_cbranch_scc1 .LBB0_293
	s_max_i32 s10, s13, 0
	s_add_i32 s14, s10, s82
	s_lshl_b32 s10, s14, 7
	v_mad_u64_u32 v[82:83], s[10:11], s10, v196, v[114:115]
	s_barrier
	s_waitcnt vmcnt(7)
	ds_write_b128 v176, v[18:21]
	s_waitcnt vmcnt(6)
	ds_write_b128 v176, v[22:25] offset:8704
	s_waitcnt vmcnt(5)
	ds_write_b128 v176, v[26:29] offset:17408
	s_waitcnt vmcnt(4)
	ds_write_b128 v176, v[34:37] offset:26112
	v_add_co_u32_e32 v22, vcc, s59, v82
	s_lshl_b32 s88, s14, 8
	s_nop 0
	v_addc_co_u32_e32 v23, vcc, 0, v83, vcc
	v_add_co_u32_e32 v26, vcc, s64, v82
	s_waitcnt vmcnt(3)
	ds_write_b128 v176, v[30:33] offset:34816
	s_waitcnt vmcnt(2)
	ds_write_b128 v176, v[38:41] offset:43520
	s_waitcnt vmcnt(1)
	ds_write_b128 v176, v[42:45] offset:52224
	s_waitcnt vmcnt(0)
	ds_write_b128 v176, v[46:49] offset:60928
	v_addc_co_u32_e32 v27, vcc, 0, v83, vcc
	v_add_co_u32_e32 v30, vcc, s65, v82
	v_lshl_add_u64 v[84:85], v[116:117], 0, s[88:89]
	s_nop 0
	v_addc_co_u32_e32 v31, vcc, 0, v83, vcc
	v_add_co_u32_e32 v38, vcc, 0x100000, v84
	s_waitcnt lgkmcnt(0)
	s_nop 0
	v_addc_co_u32_e32 v39, vcc, 0, v85, vcc
	v_add_co_u32_e32 v42, vcc, 0x200000, v84
	s_barrier
	s_nop 0
	v_addc_co_u32_e32 v43, vcc, 0, v85, vcc
	v_add_co_u32_e32 v46, vcc, 0x300000, v84
	s_nop 1
	v_addc_co_u32_e32 v47, vcc, 0, v85, vcc
	global_load_dwordx4 v[18:21], v[82:83], off offset:2048
	s_nop 0
	global_load_dwordx4 v[22:25], v[22:23], off offset:2048
	s_nop 0
	global_load_dwordx4 v[26:29], v[26:27], off offset:2048
	s_nop 0
	global_load_dwordx4 v[34:37], v[30:31], off offset:2048
	s_nop 0
	global_load_dwordx4 v[30:33], v[84:85], off
	s_nop 0
	global_load_dwordx4 v[38:41], v[38:39], off
	s_nop 0
	global_load_dwordx4 v[42:45], v[42:43], off
	v_cmp_le_f32_e32 vcc, s72, v118
	global_load_dwordx4 v[46:49], v[46:47], off
	s_cbranch_vccz .LBB0_287
	s_setprio 1
	ds_read_b128 v[128:131], v182
	ds_read_b128 v[132:135], v182 offset:64
	ds_read_b128 v[136:139], v182 offset:128
	ds_read_b128 v[140:143], v182 offset:192
	ds_read_b128 v[144:147], v182 offset:4352
	ds_read_b128 v[148:151], v182 offset:4416
	ds_read_b128 v[152:155], v182 offset:4480
	ds_read_b128 v[156:159], v182 offset:4544
	ds_read_b128 v[160:163], v182 offset:8704
	ds_read_b128 v[164:167], v182 offset:8768
	ds_read_b128 v[168:171], v182 offset:8832
	ds_read_b128 v[188:191], v182 offset:8896
	s_waitcnt lgkmcnt(11)
	v_mfma_f32_16x16x32_bf16 v[82:85], v[128:131], v[2:5], 0
	ds_read_b128 v[128:131], v182 offset:13056
	s_waitcnt lgkmcnt(11)
	v_mfma_f32_16x16x32_bf16 v[82:85], v[132:135], v[6:9], v[82:85]
	ds_read_b128 v[132:135], v182 offset:13120
	s_waitcnt lgkmcnt(11)
	v_mfma_f32_16x16x32_bf16 v[82:85], v[136:139], v[10:13], v[82:85]
	ds_read_b128 v[136:139], v182 offset:13184
	s_waitcnt lgkmcnt(11)
	v_mfma_f32_16x16x32_bf16 v[82:85], v[140:143], v[14:17], v[82:85]
	ds_read_b128 v[140:143], v182 offset:13248
	s_waitcnt lgkmcnt(11)
	v_mfma_f32_16x16x32_bf16 v[86:89], v[144:147], v[2:5], 0
	ds_read_b128 v[144:147], v182 offset:17408
	s_waitcnt lgkmcnt(11)
	v_mfma_f32_16x16x32_bf16 v[86:89], v[148:151], v[6:9], v[86:89]
	ds_read_b128 v[148:151], v182 offset:17472
	s_waitcnt lgkmcnt(11)
	v_mfma_f32_16x16x32_bf16 v[86:89], v[152:155], v[10:13], v[86:89]
	ds_read_b128 v[152:155], v182 offset:17536
	s_waitcnt lgkmcnt(11)
	v_mfma_f32_16x16x32_bf16 v[86:89], v[156:159], v[14:17], v[86:89]
	ds_read_b128 v[156:159], v182 offset:17600
	s_waitcnt lgkmcnt(11)
	v_mfma_f32_16x16x32_bf16 v[90:93], v[160:163], v[2:5], 0
	ds_read_b128 v[160:163], v182 offset:21760
	s_waitcnt lgkmcnt(11)
	v_mfma_f32_16x16x32_bf16 v[90:93], v[164:167], v[6:9], v[90:93]
	ds_read_b128 v[164:167], v182 offset:21824
	s_waitcnt lgkmcnt(11)
	v_mfma_f32_16x16x32_bf16 v[90:93], v[168:171], v[10:13], v[90:93]
	ds_read_b128 v[168:171], v182 offset:21888
	s_waitcnt lgkmcnt(11)
	v_mfma_f32_16x16x32_bf16 v[90:93], v[188:191], v[14:17], v[90:93]
	ds_read_b128 v[188:191], v182 offset:21952
	s_waitcnt lgkmcnt(11)
	v_mfma_f32_16x16x32_bf16 v[94:97], v[128:131], v[2:5], 0
	ds_read_b128 v[128:131], v182 offset:26112
	s_waitcnt lgkmcnt(11)
	v_mfma_f32_16x16x32_bf16 v[94:97], v[132:135], v[6:9], v[94:97]
	ds_read_b128 v[132:135], v182 offset:26176
	s_waitcnt lgkmcnt(11)
	v_mfma_f32_16x16x32_bf16 v[94:97], v[136:139], v[10:13], v[94:97]
	ds_read_b128 v[136:139], v182 offset:26240
	s_waitcnt lgkmcnt(11)
	v_mfma_f32_16x16x32_bf16 v[96:99], v[140:143], v[14:17], v[94:97]
	ds_read_b128 v[140:143], v182 offset:26304
	s_waitcnt lgkmcnt(11)
	v_mfma_f32_16x16x32_bf16 v[100:103], v[144:147], v[2:5], 0
	ds_read_b128 v[144:147], v182 offset:30464
	s_waitcnt lgkmcnt(11)
	v_mfma_f32_16x16x32_bf16 v[100:103], v[148:151], v[6:9], v[100:103]
	ds_read_b128 v[148:151], v182 offset:30528
	s_waitcnt lgkmcnt(11)
	v_mfma_f32_16x16x32_bf16 v[100:103], v[152:155], v[10:13], v[100:103]
	ds_read_b128 v[152:155], v182 offset:30592
	s_waitcnt lgkmcnt(11)
	v_mfma_f32_16x16x32_bf16 v[100:103], v[156:159], v[14:17], v[100:103]
	ds_read_b128 v[156:159], v182 offset:30656
	s_waitcnt lgkmcnt(11)
	v_mfma_f32_16x16x32_bf16 v[104:107], v[160:163], v[2:5], 0
	s_waitcnt lgkmcnt(10)
	v_mfma_f32_16x16x32_bf16 v[104:107], v[164:167], v[6:9], v[104:107]
	s_waitcnt lgkmcnt(9)
	v_mfma_f32_16x16x32_bf16 v[104:107], v[168:171], v[10:13], v[104:107]
	s_waitcnt lgkmcnt(8)
	v_mfma_f32_16x16x32_bf16 v[104:107], v[188:191], v[14:17], v[104:107]
	s_waitcnt lgkmcnt(7)
	v_mfma_f32_16x16x32_bf16 v[108:111], v[128:131], v[2:5], 0
	s_waitcnt lgkmcnt(6)
	v_mfma_f32_16x16x32_bf16 v[108:111], v[132:135], v[6:9], v[108:111]
	s_waitcnt lgkmcnt(5)
	v_mfma_f32_16x16x32_bf16 v[108:111], v[136:139], v[10:13], v[108:111]
	s_waitcnt lgkmcnt(4)
; __device__ __forceinline__ f32x4 mfma16(bf16x8 a, bf16x8 b, f32x4 c) { return __builtin_amdgcn_mfma_f32_16x16x32_bf16(a, b, c, 0, 0, 0); }
; __device__ __forceinline__ float ex2(float x) { return __builtin_amdgcn_exp2f(x); }
; __device__ __forceinline__ float lg2(float x) { return __builtin_amdgcn_logf(x); }
; __device__ __forceinline__ void qk_tiles(f32x4 (&s)[8], const bf16_t* Ks, const bf16x8 (&qf)[4], int fr, int g, int tlo, int thi) {
;   __builtin_amdgcn_s_setprio(1);
; #pragma unroll
;   for (int T = 0; T < 8; ++T) {
;     s[T] = (f32x4){0.f, 0.f, 0.f, 0.f};
;     if (T >= tlo && T <= thi) {
; #pragma unroll
;       for (int kc = 0; kc < 4; ++kc) {
;         bf16x8 a = *(const bf16x8*)(Ks + (T * 16 + fr) * LROW + kc * 32 + g * 8);
;         s[T] = mfma16(a, qf[kc], s[T]);
;       }
;     }
;   }
;   __builtin_amdgcn_s_setprio(0);
; }
; __device__ __forceinline__ void sb_item(KParams p, int tb, int hd) {
;     ...
;       for (int T = 0; T < 8; ++T) {
;         if (T <= thi) {
; #pragma unroll
;           for (int r = 0; r < 4; ++r) {
;             const float z2 = s[T][r] * C2;
;             const float sp = fmaxf(z2, 0.f) + lg2(1.f + ex2(-fabsf(z2)));
;             l1[T][r] = -sp;
;             s[T][r] = z2 - sp;
;           }
;         }
;       }
	v_mfma_f32_16x16x32_bf16 v[108:111], v[140:143], v[14:17], v[108:111]
	s_waitcnt lgkmcnt(3)
	v_mfma_f32_16x16x32_bf16 v[120:123], v[144:147], v[2:5], 0
	s_waitcnt lgkmcnt(2)
	v_mfma_f32_16x16x32_bf16 v[120:123], v[148:151], v[6:9], v[120:123]
	s_waitcnt lgkmcnt(1)
	v_mfma_f32_16x16x32_bf16 v[120:123], v[152:155], v[10:13], v[120:123]
	s_waitcnt lgkmcnt(0)
	v_mfma_f32_16x16x32_bf16 v[184:187], v[156:159], v[14:17], v[120:123]
	s_setprio 0
	s_nop 3
	v_mul_f32_e32 v120, 0x3e0293ee, v83
	v_mul_f32_e32 v82, 0x3e0293ee, v82
	v_exp_f32_e64 v83, -|v120|
	v_exp_f32_e64 v94, -|v82|
	v_mul_f32_e32 v122, 0x3e0293ee, v84
	v_mul_f32_e32 v84, 0x3e0293ee, v85
	v_add_f32_e32 v83, 1.0, v83
	v_add_f32_e32 v94, 1.0, v94
	v_log_f32_e32 v133, v83
	v_exp_f32_e64 v83, -|v122|
	v_log_f32_e32 v135, v94
	v_exp_f32_e64 v94, -|v84|
	v_mul_f32_e32 v124, 0x3e0293ee, v86
	v_add_f32_e32 v83, 1.0, v83
	v_log_f32_e32 v134, v83
	v_add_f32_e32 v83, 1.0, v94
	v_log_f32_e32 v132, v83
	v_exp_f32_e64 v83, -|v124|
	v_mul_f32_e32 v126, 0x3e0293ee, v87
	v_max_f32_e32 v128, 0, v84
	v_exp_f32_e64 v84, -|v126|
	v_add_f32_e32 v83, 1.0, v83
	v_log_f32_e32 v143, v83
	v_mul_f32_e32 v88, 0x3e0293ee, v88
	v_add_f32_e32 v83, 1.0, v84
	v_log_f32_e32 v141, v83
	v_exp_f32_e64 v83, -|v88|
	v_mul_f32_e32 v84, 0x3e0293ee, v89
	v_exp_f32_e64 v94, -|v84|
	v_mul_f32_e32 v90, 0x3e0293ee, v90
	v_add_f32_e32 v83, 1.0, v83
	v_log_f32_e32 v142, v83
	v_add_f32_e32 v83, 1.0, v94
	v_log_f32_e32 v140, v83
	v_exp_f32_e64 v83, -|v90|
	v_mul_f32_e32 v136, 0x3e0293ee, v91
	v_max_f32_e32 v86, 0, v84
	v_exp_f32_e64 v84, -|v136|
	v_add_f32_e32 v83, 1.0, v83
	v_log_f32_e32 v153, v83
	v_mul_f32_e32 v92, 0x3e0293ee, v92
	v_add_f32_e32 v83, 1.0, v84
	v_log_f32_e32 v151, v83
	v_exp_f32_e64 v83, -|v92|
	v_mul_f32_e32 v84, 0x3e0293ee, v93
	v_exp_f32_e64 v91, -|v84|
	v_mul_f32_e32 v154, 0x3e0293ee, v96
	v_add_f32_e32 v83, 1.0, v83
	v_log_f32_e32 v152, v83
	v_add_f32_e32 v83, 1.0, v91
	v_log_f32_e32 v150, v83
	v_exp_f32_e64 v83, -|v154|
	v_mul_f32_e32 v156, 0x3e0293ee, v97
	v_max_f32_e32 v148, 0, v84
	v_exp_f32_e64 v84, -|v156|
	v_add_f32_e32 v83, 1.0, v83
	v_log_f32_e32 v167, v83
	v_mul_f32_e32 v158, 0x3e0293ee, v98
	v_add_f32_e32 v83, 1.0, v84
	v_log_f32_e32 v165, v83
	v_exp_f32_e64 v83, -|v158|
	v_mul_f32_e32 v84, 0x3e0293ee, v99
	v_exp_f32_e64 v91, -|v84|
	v_mul_f32_e32 v98, 0x3e0293ee, v100
	v_add_f32_e32 v83, 1.0, v83
	v_log_f32_e32 v166, v83
	v_add_f32_e32 v83, 1.0, v91
	v_log_f32_e32 v164, v83
	v_exp_f32_e64 v83, -|v98|
	v_mul_f32_e32 v100, 0x3e0293ee, v101
	v_max_f32_e32 v162, 0, v84
	v_exp_f32_e64 v84, -|v100|
	v_add_f32_e32 v83, 1.0, v83
	v_log_f32_e32 v146, v83
	v_mul_f32_e32 v102, 0x3e0293ee, v102
	v_add_f32_e32 v83, 1.0, v84
	v_log_f32_e32 v188, v83
	v_exp_f32_e64 v83, -|v102|
	v_mul_f32_e32 v84, 0x3e0293ee, v103
	v_exp_f32_e64 v91, -|v84|
	v_mul_f32_e32 v104, 0x3e0293ee, v104
	v_add_f32_e32 v83, 1.0, v83
	v_log_f32_e32 v147, v83
	v_add_f32_e32 v83, 1.0, v91
	v_log_f32_e32 v189, v83
	v_exp_f32_e64 v83, -|v104|
	v_mul_f32_e32 v168, 0x3e0293ee, v105
	v_max_f32_e32 v171, 0, v84
	v_exp_f32_e64 v84, -|v168|
	v_add_f32_e32 v83, 1.0, v83
	v_log_f32_e32 v200, v83
	v_mul_f32_e32 v106, 0x3e0293ee, v106
	v_add_f32_e32 v83, 1.0, v84
	v_log_f32_e32 v204, v83
	v_exp_f32_e64 v83, -|v106|
	v_mul_f32_e32 v84, 0x3e0293ee, v107
	v_exp_f32_e64 v91, -|v84|
	v_mul_f32_e32 v108, 0x3e0293ee, v108
	v_add_f32_e32 v83, 1.0, v83
	v_log_f32_e32 v201, v83
	v_add_f32_e32 v83, 1.0, v91
	v_log_f32_e32 v205, v83
	v_exp_f32_e64 v83, -|v108|
	v_mul_f32_e32 v206, 0x3e0293ee, v109
	v_max_f32_e32 v203, 0, v84
	v_exp_f32_e64 v84, -|v206|
	v_add_f32_e32 v83, 1.0, v83
	v_mul_f32_e32 v184, 0x3e0293ee, v184
	v_log_f32_e32 v208, v83
	v_add_f32_e32 v83, 1.0, v84
	v_exp_f32_e64 v84, -|v184|
	v_mul_f32_e32 v216, 0x3e0293ee, v185
	v_exp_f32_e64 v91, -|v216|
	v_mul_f32_e32 v186, 0x3e0293ee, v186
	v_add_f32_e32 v84, 1.0, v84
	v_log_f32_e32 v218, v84
	v_add_f32_e32 v84, 1.0, v91
	v_exp_f32_e64 v91, -|v186|
	v_mul_f32_e32 v101, 0x3e0293ee, v187
	v_exp_f32_e64 v105, -|v101|
	v_log_f32_e32 v222, v84
	v_add_f32_e32 v84, 1.0, v91
	v_log_f32_e32 v219, v84
	v_add_f32_e32 v84, 1.0, v105
	v_log_f32_e32 v223, v84
	v_max_f32_e32 v214, 0, v184
	v_max_f32_e32 v220, 0, v216
	v_max_f32_e32 v215, 0, v186
	v_max_f32_e32 v221, 0, v101
	v_pk_add_f32 v[214:215], v[214:215], v[218:219]
	v_pk_add_f32 v[218:219], v[220:221], v[222:223]
	v_mul_f32_e32 v110, 0x3e0293ee, v110
	v_pk_add_f32 v[220:221], v[218:219], v[214:215] neg_lo:[1,1] neg_hi:[1,1]
	v_log_f32_e32 v212, v83
	v_add_f32_e32 v84, v220, v221
	ds_bpermute_b32 v91, v178, v84
	v_exp_f32_e64 v83, -|v110|
	v_mov_b32_e32 v220, v215
	v_mov_b32_e32 v221, v219
	v_max_f32_e32 v96, 0, v108
	s_waitcnt lgkmcnt(0)
	v_cndmask_b32_e64 v91, v91, 0, s[4:5]
	v_add_f32_e32 v83, 1.0, v83
	v_add_f32_e32 v91, v91, v84
	v_log_f32_e32 v209, v83
	v_mul_f32_e32 v83, 0x3e0293ee, v111
	ds_bpermute_b32 v105, v179, v91
	v_exp_f32_e64 v101, -|v83|
	v_max_f32_e32 v211, 0, v83
	v_max_f32_e32 v210, 0, v206
	v_max_f32_e32 v97, 0, v110
	v_add_f32_e32 v83, 1.0, v101
	s_waitcnt lgkmcnt(0)
	v_cndmask_b32_e64 v101, 0, v105, s[6:7]
	v_add_f32_e32 v91, v101, v91
	v_sub_f32_e32 v84, v91, v84
	v_log_f32_e32 v213, v83
	v_fma_f32 v83, v187, s92, -v219
	v_add_f32_e32 v187, v118, v84
	v_add_f32_e32 v83, v83, v187
	v_pk_add_f32 v[186:187], v[186:187], v[220:221] neg_lo:[0,1] neg_hi:[0,1]
	v_mov_b32_e32 v219, v215
	v_mov_b32_e32 v217, v187
	v_add_f32_e32 v84, v186, v187
	v_pk_add_f32 v[186:187], v[216:217], v[218:219] neg_lo:[0,1] neg_hi:[0,1]
	v_mov_b32_e32 v215, v218
	v_add_f32_e32 v101, v186, v187
	v_mov_b32_e32 v185, v187
	v_pk_add_f32 v[186:187], v[96:97], v[208:209]
	v_pk_add_f32 v[208:209], v[210:211], v[212:213]
	v_exp_f32_e32 v83, v83
	v_pk_add_f32 v[96:97], v[208:209], v[186:187] neg_lo:[1,1] neg_hi:[1,1]
	v_exp_f32_e32 v84, v84
	v_pk_add_f32 v[210:211], v[96:97], v[96:97] op_sel:[0,1] op_sel_hi:[1,0]
	ds_bpermute_b32 v105, v178, v210
	v_pk_add_f32 v[96:97], v[184:185], v[214:215] neg_lo:[0,1] neg_hi:[0,1]
	ds_bpermute_b32 v184, v180, v91
	v_add_f32_e32 v96, v96, v97
	v_exp_f32_e32 v101, v101
	s_waitcnt lgkmcnt(1)
; __device__ __forceinline__ float shfl_lane(float x, int src_lane) { return __int_as_float(__builtin_amdgcn_ds_bpermute(src_lane << 2, __float_as_int(x))); }
; __device__ __forceinline__ float ex2(float x) { return __builtin_amdgcn_exp2f(x); }
; __device__ __forceinline__ void sb_item(KParams p, int tb, int hd) {
;     ...
;       for (int T = 7; T >= 0; --T) {
;         if (T <= thi) {
;           const float x = (l1[T][0] + l1[T][1]) + (l1[T][2] + l1[T][3]);
;           float a = shfl_lane(x, (lane + 16) & 63); a = (g < 3) ? a : 0.f;
;           const float y1 = x + a;
;           float b2 = shfl_lane(y1, (lane + 32) & 63); b2 = (g < 2) ? b2 : 0.f;
;           const float incl = y1 + b2;
;           const float tt = shfl_lane(incl, fr);
;           float base = running + (incl - x);
;           const float w3 = ex2(s[T][3] + base); base += l1[T][3];
;           const float w2 = ex2(s[T][2] + base); base += l1[T][2];
;           const float w1 = ex2(s[T][1] + base); base += l1[T][1];
;           const float w0 = ex2(s[T][0] + base);
;           set_pf(pf, T, w0, w1, w2, w3);
;           running += tt;
;         }
;       }
	v_cndmask_b32_e64 v97, v105, 0, s[4:5]
	v_add_f32_e32 v119, v210, v97
	ds_bpermute_b32 v105, v179, v119
	v_cvt_pk_bf16_f32 v97, v84, v83
	v_fma_f32 v83, v111, s92, -v209
	v_exp_f32_e32 v96, v96
	v_max_f32_e32 v190, 0, v104
	s_waitcnt lgkmcnt(0)
	v_cndmask_b32_e64 v185, 0, v105, s[6:7]
	v_pk_add_f32 v[118:119], v[118:119], v[184:185]
	v_max_f32_e32 v202, 0, v168
	v_pk_add_f32 v[210:211], v[118:119], v[210:211] op_sel:[1,0] op_sel_hi:[0,1] neg_lo:[0,1] neg_hi:[0,1]
	v_pk_add_f32 v[210:211], v[118:119], v[210:211]
	v_max_f32_e32 v191, 0, v106
	v_add_f32_e32 v83, v83, v210
	v_mov_b32_e32 v111, v210
	v_mov_b32_e32 v210, v187
	v_mov_b32_e32 v211, v209
	v_pk_add_f32 v[110:111], v[110:111], v[210:211] neg_lo:[0,1] neg_hi:[0,1]
	v_mov_b32_e32 v209, v187
	v_mov_b32_e32 v207, v111
	v_add_f32_e32 v84, v110, v111
	v_pk_add_f32 v[110:111], v[206:207], v[208:209] neg_lo:[0,1] neg_hi:[0,1]
	v_mov_b32_e32 v187, v208
	v_add_f32_e32 v91, v110, v111
	v_mov_b32_e32 v109, v111
	v_pk_add_f32 v[110:111], v[190:191], v[200:201]
	v_pk_add_f32 v[190:191], v[202:203], v[204:205]
	v_pk_add_f32 v[108:109], v[108:109], v[186:187] neg_lo:[0,1] neg_hi:[0,1]
	v_pk_add_f32 v[200:201], v[190:191], v[110:111] neg_lo:[1,1] neg_hi:[1,1]
	v_max_f32_e32 v94, 0, v98
	v_max_f32_e32 v170, 0, v100
	v_max_f32_e32 v95, 0, v102
	v_cvt_pk_bf16_f32 v96, v96, v101
	v_add_f32_e32 v101, v200, v201
	v_add_f32_e32 v108, v108, v109
	ds_bpermute_b32 v184, v180, v119
	ds_bpermute_b32 v105, v178, v101
	v_exp_f32_e32 v119, v108
	v_pk_add_f32 v[108:109], v[94:95], v[146:147]
	v_pk_add_f32 v[146:147], v[170:171], v[188:189]
	v_exp_f32_e32 v91, v91
	v_pk_add_f32 v[94:95], v[146:147], v[108:109] neg_lo:[1,1] neg_hi:[1,1]
	s_waitcnt lgkmcnt(0)
	v_cndmask_b32_e64 v105, v105, 0, s[4:5]
	v_add_f32_e32 v123, v94, v95
	ds_bpermute_b32 v125, v178, v123
	v_exp_f32_e32 v83, v83
	v_exp_f32_e32 v84, v84
	v_add_f32_e32 v105, v101, v105
	ds_bpermute_b32 v121, v179, v105
	v_cvt_pk_bf16_f32 v94, v119, v91
	s_waitcnt lgkmcnt(1)
	v_cndmask_b32_e64 v91, v125, 0, s[4:5]
	v_add_f32_e32 v91, v123, v91
	v_max_f32_e32 v161, 0, v154
	v_max_f32_e32 v163, 0, v156
	v_max_f32_e32 v160, 0, v158
	v_cvt_pk_bf16_f32 v95, v84, v83
	v_fma_f32 v83, v107, s92, -v191
	ds_bpermute_b32 v107, v179, v91
	v_pk_add_f32 v[160:161], v[160:161], v[166:167]
	v_pk_add_f32 v[162:163], v[162:163], v[164:165]
	s_waitcnt lgkmcnt(1)
	v_cndmask_b32_e64 v84, 0, v121, s[6:7]
	v_pk_add_f32 v[164:165], v[160:161], v[162:163] neg_lo:[1,1] neg_hi:[1,1]
	v_add_f32_e32 v84, v105, v84
	v_mov_b32_e32 v119, v164
	v_mov_b32_e32 v185, v165
	ds_bpermute_b32 v170, v180, v84
	v_sub_f32_e32 v84, v84, v101
	v_pk_add_f32 v[118:119], v[118:119], v[184:185]
	v_fma_f32 v101, v103, s92, -v147
	s_waitcnt lgkmcnt(1)
	v_cndmask_b32_e64 v103, 0, v107, s[6:7]
	v_add_f32_e32 v107, v118, v84
	v_mov_b32_e32 v164, v111
	v_mov_b32_e32 v165, v191
	v_add_f32_e32 v83, v83, v107
	v_pk_add_f32 v[106:107], v[106:107], v[164:165] neg_lo:[0,1] neg_hi:[0,1]
	v_mov_b32_e32 v191, v111
	v_mov_b32_e32 v169, v107
	v_add_f32_e32 v84, v106, v107
	v_pk_add_f32 v[106:107], v[168:169], v[190:191] neg_lo:[0,1] neg_hi:[0,1]
	v_add_f32_e32 v91, v91, v103
	v_fma_f32 v121, v99, s92, -v162
	v_add_f32_e32 v99, v106, v107
	ds_bpermute_b32 v186, v180, v91
	v_sub_f32_e32 v91, v91, v123
	v_exp_f32_e32 v123, v99
	ds_bpermute_b32 v99, v178, v119
	v_mov_b32_e32 v105, v107
	v_mov_b32_e32 v111, v190
	v_pk_add_f32 v[104:105], v[104:105], v[110:111] neg_lo:[0,1] neg_hi:[0,1]
	v_mov_b32_e32 v106, v109
	s_waitcnt lgkmcnt(0)
	v_cndmask_b32_e64 v171, v99, 0, s[4:5]
	v_add_f32_e32 v103, v104, v105
	v_pk_add_f32 v[104:105], v[118:119], v[170:171]
	v_exp_f32_e32 v110, v103
	v_add_f32_e32 v103, v104, v91
	v_mov_b32_e32 v107, v147
	v_add_f32_e32 v91, v101, v103
	v_pk_add_f32 v[102:103], v[102:103], v[106:107] neg_lo:[0,1] neg_hi:[0,1]
	v_mov_b32_e32 v147, v109
	v_mov_b32_e32 v101, v103
	v_add_f32_e32 v99, v102, v103
	v_pk_add_f32 v[100:101], v[100:101], v[146:147] neg_lo:[0,1] neg_hi:[0,1]
	v_exp_f32_e32 v102, v99
	v_add_f32_e32 v99, v100, v101
	v_exp_f32_e32 v103, v99
	v_mov_b32_e32 v99, v101
	v_mov_b32_e32 v109, v146
	v_pk_add_f32 v[98:99], v[98:99], v[108:109] neg_lo:[0,1] neg_hi:[0,1]
	ds_bpermute_b32 v106, v179, v105
	v_add_f32_e32 v98, v98, v99
	v_exp_f32_e32 v91, v91
	v_exp_f32_e32 v98, v98
	v_exp_f32_e32 v83, v83
	v_exp_f32_e32 v84, v84
	s_waitcnt lgkmcnt(0)
	v_cndmask_b32_e64 v187, 0, v106, s[6:7]
	v_cvt_pk_bf16_f32 v98, v98, v103
	v_cvt_pk_bf16_f32 v99, v102, v91
	v_pk_add_f32 v[102:103], v[104:105], v[186:187]
	v_cvt_pk_bf16_f32 v101, v84, v83
	v_sub_f32_e32 v84, v103, v119
	v_pk_add_f32 v[106:107], v[102:103], v[84:85] op_sel_hi:[1,0]
	v_max_f32_e32 v145, 0, v90
	v_add_f32_e32 v83, v121, v106
	v_mov_b32_e32 v159, v106
	v_mov_b32_e32 v106, v160
	v_mov_b32_e32 v107, v162
	v_pk_add_f32 v[106:107], v[158:159], v[106:107] neg_lo:[0,1] neg_hi:[0,1]
	v_max_f32_e32 v149, 0, v136
	v_add_f32_e32 v84, v106, v107
	v_mov_b32_e32 v157, v107
	v_pk_mov_b32 v[106:107], v[162:163], v[160:161] op_sel:[1,0]
	v_max_f32_e32 v144, 0, v92
	v_pk_add_f32 v[106:107], v[156:157], v[106:107] neg_lo:[0,1] neg_hi:[0,1]
	v_pk_add_f32 v[108:109], v[148:149], v[150:151]
	v_add_f32_e32 v91, v106, v107
	v_mov_b32_e32 v155, v107
	v_pk_add_f32 v[106:107], v[144:145], v[152:153]
	v_cvt_pk_bf16_f32 v100, v110, v123
	v_pk_add_f32 v[110:111], v[106:107], v[108:109] neg_lo:[1,1] neg_hi:[1,1]
	v_mov_b32_e32 v162, v161
	ds_bpermute_b32 v104, v180, v103
	v_add_f32_e32 v103, v110, v111
	v_pk_add_f32 v[110:111], v[154:155], v[162:163] neg_lo:[0,1] neg_hi:[0,1]
	v_max_f32_e32 v139, 0, v124
	v_max_f32_e32 v87, 0, v126
	v_max_f32_e32 v138, 0, v88
	ds_bpermute_b32 v105, v178, v103
	v_add_f32_e32 v110, v110, v111
	v_exp_f32_e32 v121, v110
	v_pk_add_f32 v[110:111], v[138:139], v[142:143]
	v_pk_add_f32 v[118:119], v[86:87], v[140:141]
	v_exp_f32_e32 v91, v91
	v_pk_add_f32 v[86:87], v[110:111], v[118:119] neg_lo:[1,1] neg_hi:[1,1]
	s_waitcnt lgkmcnt(0)
; __device__ __forceinline__ float shfl_lane(float x, int src_lane) { return __int_as_float(__builtin_amdgcn_ds_bpermute(src_lane << 2, __float_as_int(x))); }
; __device__ __forceinline__ f32x4 mfma16(bf16x8 a, bf16x8 b, f32x4 c) { return __builtin_amdgcn_mfma_f32_16x16x32_bf16(a, b, c, 0, 0, 0); }
; __device__ __forceinline__ float ex2(float x) { return __builtin_amdgcn_exp2f(x); }
; __device__ __forceinline__ void pv_tiles(f32x4 (&o)[8], const bf16_t* Vts, const bf16x8 (&pf)[4], int fr, int g, int tlo, int thi) {
;   __builtin_amdgcn_s_setprio(1);
; #pragma unroll
;   for (int kc = 0; kc < 4; ++kc) {
;     if (2 * kc + 1 >= tlo && 2 * kc <= thi) {
; #pragma unroll
;       for (int dt = 0; dt < 8; ++dt) {
;         const bf16_t* vp = Vts + (dt * 16 + fr) * LROW + kc * 32 + g * 4;
;         bf16x4 lo = *(const bf16x4*)vp, hi = *(const bf16x4*)(vp + 16);
;         bf16x8 a = __builtin_shufflevector(lo, hi, 0, 1, 2, 3, 4, 5, 6, 7);
;         o[dt] = mfma16(a, pf[kc], o[dt]);
;       }
; __device__ __forceinline__ void sb_item(KParams p, int tb, int hd) {
;     ...
;       for (int T = 7; T >= 0; --T) {
;         if (T <= thi) {
;           const float x = (l1[T][0] + l1[T][1]) + (l1[T][2] + l1[T][3]);
;           float a = shfl_lane(x, (lane + 16) & 63); a = (g < 3) ? a : 0.f;
;           const float y1 = x + a;
;           float b2 = shfl_lane(y1, (lane + 32) & 63); b2 = (g < 2) ? b2 : 0.f;
;           const float incl = y1 + b2;
;           const float tt = shfl_lane(incl, fr);
;           float base = running + (incl - x);
;           const float w3 = ex2(s[T][3] + base); base += l1[T][3];
;           const float w2 = ex2(s[T][2] + base); base += l1[T][2];
;           const float w1 = ex2(s[T][1] + base); base += l1[T][1];
;           const float w0 = ex2(s[T][0] + base);
;           set_pf(pf, T, w0, w1, w2, w3);
;           running += tt;
;         }
;       }
;       carry = running;
;       pv_tiles(o, Vts, pf, fr, g, 0, thi);
	v_cndmask_b32_e64 v105, v105, 0, s[4:5]
	v_add_f32_e32 v125, v86, v87
	ds_bpermute_b32 v127, v178, v125
	v_add_f32_e32 v105, v103, v105
	v_exp_f32_e32 v83, v83
	v_exp_f32_e32 v84, v84
	ds_bpermute_b32 v123, v179, v105
	v_cvt_pk_bf16_f32 v86, v121, v91
	s_waitcnt lgkmcnt(1)
	v_cndmask_b32_e64 v91, v127, 0, s[4:5]
	v_add_f32_e32 v91, v125, v91
	v_max_f32_e32 v131, 0, v82
	v_max_f32_e32 v129, 0, v120
	v_max_f32_e32 v130, 0, v122
	v_cvt_pk_bf16_f32 v87, v84, v83
	v_fma_f32 v83, v93, s92, -v108
	ds_bpermute_b32 v93, v179, v91
	s_waitcnt lgkmcnt(1)
	v_cndmask_b32_e64 v84, 0, v123, s[6:7]
	v_pk_add_f32 v[130:131], v[130:131], v[134:135]
	v_pk_add_f32 v[128:129], v[128:129], v[132:133]
	v_add_f32_e32 v84, v105, v84
	v_pk_add_f32 v[132:133], v[130:131], v[128:129] neg_lo:[1,1] neg_hi:[1,1]
	ds_bpermute_b32 v138, v180, v84
	v_sub_f32_e32 v84, v84, v103
	v_mov_b32_e32 v103, v132
	v_mov_b32_e32 v105, v133
	v_pk_add_f32 v[102:103], v[102:103], v[104:105]
	v_fma_f32 v121, v89, s92, -v118
	s_waitcnt lgkmcnt(1)
	v_cndmask_b32_e64 v89, 0, v93, s[6:7]
	v_add_f32_e32 v93, v102, v84
	v_mov_b32_e32 v104, v106
	v_mov_b32_e32 v105, v108
	v_add_f32_e32 v83, v83, v93
	v_pk_add_f32 v[92:93], v[92:93], v[104:105] neg_lo:[0,1] neg_hi:[0,1]
	v_add_f32_e32 v89, v91, v89
	v_add_f32_e32 v84, v92, v93
	v_mov_b32_e32 v137, v93
	v_pk_mov_b32 v[92:93], v[108:109], v[106:107] op_sel:[1,0]
	v_exp_f32_e32 v123, v84
	v_pk_add_f32 v[92:93], v[136:137], v[92:93] neg_lo:[0,1] neg_hi:[0,1]
	v_mov_b32_e32 v108, v107
	v_add_f32_e32 v84, v92, v93
	ds_bpermute_b32 v92, v178, v103
	v_mov_b32_e32 v91, v93
	v_pk_add_f32 v[90:91], v[90:91], v[108:109] neg_lo:[0,1] neg_hi:[0,1]
	ds_bpermute_b32 v140, v180, v89
	v_sub_f32_e32 v89, v89, v125
	s_waitcnt lgkmcnt(1)
	v_cndmask_b32_e64 v139, v92, 0, s[4:5]
	v_add_f32_e32 v90, v90, v91
	v_pk_add_f32 v[92:93], v[102:103], v[138:139]
	v_exp_f32_e32 v108, v90
	v_add_f32_e32 v89, v92, v89
	v_mov_b32_e32 v90, v110
	v_mov_b32_e32 v91, v118
	v_pk_add_f32 v[104:105], v[88:89], v[90:91] neg_lo:[0,1] neg_hi:[0,1]
	v_pk_mov_b32 v[90:91], v[118:119], v[110:111] op_sel:[1,0]
	v_mov_b32_e32 v127, v105
	v_exp_f32_e32 v83, v83
	v_pk_add_f32 v[90:91], v[126:127], v[90:91] neg_lo:[0,1] neg_hi:[0,1]
	v_mov_b32_e32 v118, v111
	v_mov_b32_e32 v125, v91
	v_pk_add_f32 v[106:107], v[124:125], v[118:119] neg_lo:[0,1] neg_hi:[0,1]
	v_add_f32_e32 v90, v90, v91
	v_add_f32_e32 v88, v106, v107
	v_exp_f32_e32 v88, v88
	v_exp_f32_e32 v90, v90
	v_fma_f32 v91, v85, s92, -v128
	v_cvt_pk_bf16_f32 v85, v123, v83
	ds_bpermute_b32 v83, v179, v93
	v_cvt_pk_bf16_f32 v90, v88, v90
	v_add_f32_e32 v88, v104, v105
	v_exp_f32_e32 v106, v88
	v_add_f32_e32 v88, v121, v89
	s_waitcnt lgkmcnt(0)
	v_cndmask_b32_e64 v141, 0, v83, s[6:7]
	v_exp_f32_e32 v107, v88
	v_pk_add_f32 v[88:89], v[92:93], v[140:141]
	v_mov_b32_e32 v102, v130
	v_sub_f32_e32 v92, v89, v103
	v_pk_add_f32 v[92:93], v[88:89], v[92:93] op_sel_hi:[1,0]
	v_mov_b32_e32 v103, v128
	v_mov_b32_e32 v123, v92
	v_exp_f32_e32 v84, v84
	v_pk_add_f32 v[102:103], v[122:123], v[102:103] neg_lo:[0,1] neg_hi:[0,1]
	v_pk_mov_b32 v[104:105], v[128:129], v[130:131] op_sel:[1,0]
	v_mov_b32_e32 v121, v103
	v_pk_add_f32 v[104:105], v[120:121], v[104:105] neg_lo:[0,1] neg_hi:[0,1]
	v_mov_b32_e32 v128, v131
	v_mov_b32_e32 v83, v105
	v_cvt_pk_bf16_f32 v84, v108, v84
	ds_bpermute_b32 v108, v180, v89
	v_pk_add_f32 v[82:83], v[82:83], v[128:129] neg_lo:[0,1] neg_hi:[0,1]
	v_add_f32_e32 v89, v102, v103
	v_add_f32_e32 v82, v82, v83
	v_add_f32_e32 v83, v104, v105
	v_add_f32_e32 v91, v91, v92
	v_exp_f32_e32 v82, v82
	v_exp_f32_e32 v83, v83
	v_exp_f32_e32 v89, v89
	v_exp_f32_e32 v92, v91
	s_waitcnt lgkmcnt(0)
	v_add_f32_e32 v118, v88, v108
	v_cvt_pk_bf16_f32 v91, v106, v107
	v_cvt_pk_bf16_f32 v88, v82, v83
	v_cvt_pk_bf16_f32 v89, v89, v92
	s_setprio 1
	v_add_u32_e32 v92, 0x8800, v181
	v_add_u32_e32 v93, 0x9800, v181
	v_add_u32_e32 v106, 0xa800, v181
	v_add_u32_e32 v107, 0xb800, v181
	v_add_u32_e32 v108, 0xc800, v181
	v_add_u32_e32 v109, 0xd800, v181
	v_add_u32_e32 v110, 0xe800, v181
	v_add_u32_e32 v111, 0xf800, v181
	ds_read2_b64 v[128:131], v92 offset1:4
	ds_read2_b64 v[132:135], v93 offset0:32 offset1:36
	ds_read2_b64 v[136:139], v106 offset0:64 offset1:68
	ds_read2_b64 v[140:143], v107 offset0:96 offset1:100
	ds_read2_b64 v[144:147], v108 offset0:128 offset1:132
	ds_read2_b64 v[148:151], v109 offset0:160 offset1:164
	ds_read2_b64 v[152:155], v110 offset0:192 offset1:196
	ds_read2_b64 v[156:159], v111 offset0:224 offset1:228
	ds_read2_b64 v[160:163], v92 offset0:8 offset1:12
	ds_read2_b64 v[164:167], v93 offset0:40 offset1:44
	ds_read2_b64 v[168:171], v106 offset0:72 offset1:76
	ds_read2_b64 v[188:191], v107 offset0:104 offset1:108
	s_waitcnt lgkmcnt(11)
; __device__ __forceinline__ f32x4 mfma16(bf16x8 a, bf16x8 b, f32x4 c) { return __builtin_amdgcn_mfma_f32_16x16x32_bf16(a, b, c, 0, 0, 0); }
; __device__ __forceinline__ void pv_tiles(f32x4 (&o)[8], const bf16_t* Vts, const bf16x8 (&pf)[4], int fr, int g, int tlo, int thi) {
;   __builtin_amdgcn_s_setprio(1);
; #pragma unroll
;   for (int kc = 0; kc < 4; ++kc) {
;     if (2 * kc + 1 >= tlo && 2 * kc <= thi) {
; #pragma unroll
;       for (int dt = 0; dt < 8; ++dt) {
;         const bf16_t* vp = Vts + (dt * 16 + fr) * LROW + kc * 32 + g * 4;
;         bf16x4 lo = *(const bf16x4*)vp, hi = *(const bf16x4*)(vp + 16);
;         bf16x8 a = __builtin_shufflevector(lo, hi, 0, 1, 2, 3, 4, 5, 6, 7);
;         o[dt] = mfma16(a, pf[kc], o[dt]);
;       }
;     }
;   }
;   __builtin_amdgcn_s_setprio(0);
; }
	v_mfma_f32_16x16x32_bf16 v[78:81], v[128:131], v[88:91], v[78:81]
	ds_read2_b64 v[128:131], v108 offset0:136 offset1:140
	s_waitcnt lgkmcnt(11)
	v_mfma_f32_16x16x32_bf16 v[74:77], v[132:135], v[88:91], v[74:77]
	ds_read2_b64 v[132:135], v109 offset0:168 offset1:172
	s_waitcnt lgkmcnt(11)
	v_mfma_f32_16x16x32_bf16 v[70:73], v[136:139], v[88:91], v[70:73]
	ds_read2_b64 v[136:139], v110 offset0:200 offset1:204
	s_waitcnt lgkmcnt(11)
	v_mfma_f32_16x16x32_bf16 v[66:69], v[140:143], v[88:91], v[66:69]
	ds_read2_b64 v[140:143], v111 offset0:232 offset1:236
	s_waitcnt lgkmcnt(11)
	v_mfma_f32_16x16x32_bf16 v[62:65], v[144:147], v[88:91], v[62:65]
	ds_read2_b64 v[144:147], v92 offset0:16 offset1:20
	s_waitcnt lgkmcnt(11)
	v_mfma_f32_16x16x32_bf16 v[58:61], v[148:151], v[88:91], v[58:61]
	ds_read2_b64 v[148:151], v93 offset0:48 offset1:52
	s_waitcnt lgkmcnt(11)
	v_mfma_f32_16x16x32_bf16 v[54:57], v[152:155], v[88:91], v[54:57]
	ds_read2_b64 v[152:155], v106 offset0:80 offset1:84
	s_waitcnt lgkmcnt(11)
	v_mfma_f32_16x16x32_bf16 v[50:53], v[156:159], v[88:91], v[50:53]
	ds_read2_b64 v[156:159], v107 offset0:112 offset1:116
	s_waitcnt lgkmcnt(11)
	v_mfma_f32_16x16x32_bf16 v[78:81], v[160:163], v[84:87], v[78:81]
	ds_read2_b64 v[160:163], v108 offset0:144 offset1:148
	s_waitcnt lgkmcnt(11)
	v_mfma_f32_16x16x32_bf16 v[74:77], v[164:167], v[84:87], v[74:77]
	ds_read2_b64 v[164:167], v109 offset0:176 offset1:180
	s_waitcnt lgkmcnt(11)
	v_mfma_f32_16x16x32_bf16 v[70:73], v[168:171], v[84:87], v[70:73]
	ds_read2_b64 v[168:171], v110 offset0:208 offset1:212
	s_waitcnt lgkmcnt(11)
	v_mfma_f32_16x16x32_bf16 v[66:69], v[188:191], v[84:87], v[66:69]
	ds_read2_b64 v[188:191], v111 offset0:240 offset1:244
	s_waitcnt lgkmcnt(11)
	v_mfma_f32_16x16x32_bf16 v[62:65], v[128:131], v[84:87], v[62:65]
	ds_read2_b64 v[128:131], v92 offset0:24 offset1:28
	s_waitcnt lgkmcnt(11)
	v_mfma_f32_16x16x32_bf16 v[58:61], v[132:135], v[84:87], v[58:61]
	ds_read2_b64 v[132:135], v93 offset0:56 offset1:60
	s_waitcnt lgkmcnt(11)
	v_mfma_f32_16x16x32_bf16 v[54:57], v[136:139], v[84:87], v[54:57]
	ds_read2_b64 v[136:139], v106 offset0:88 offset1:92
	s_waitcnt lgkmcnt(11)
	v_mfma_f32_16x16x32_bf16 v[50:53], v[140:143], v[84:87], v[50:53]
	ds_read2_b64 v[140:143], v107 offset0:120 offset1:124
	s_waitcnt lgkmcnt(11)
	v_mfma_f32_16x16x32_bf16 v[78:81], v[144:147], v[98:101], v[78:81]
	ds_read2_b64 v[144:147], v108 offset0:152 offset1:156
	s_waitcnt lgkmcnt(11)
	v_mfma_f32_16x16x32_bf16 v[74:77], v[148:151], v[98:101], v[74:77]
	ds_read2_b64 v[148:151], v109 offset0:184 offset1:188
	s_waitcnt lgkmcnt(11)
	v_mfma_f32_16x16x32_bf16 v[70:73], v[152:155], v[98:101], v[70:73]
	ds_read2_b64 v[152:155], v110 offset0:216 offset1:220
	s_waitcnt lgkmcnt(11)
	v_mfma_f32_16x16x32_bf16 v[66:69], v[156:159], v[98:101], v[66:69]
	ds_read2_b64 v[156:159], v111 offset0:248 offset1:252
	s_waitcnt lgkmcnt(11)
	v_mfma_f32_16x16x32_bf16 v[62:65], v[160:163], v[98:101], v[62:65]
	s_waitcnt lgkmcnt(10)
	v_mfma_f32_16x16x32_bf16 v[58:61], v[164:167], v[98:101], v[58:61]
	s_waitcnt lgkmcnt(9)
	v_mfma_f32_16x16x32_bf16 v[54:57], v[168:171], v[98:101], v[54:57]
	s_waitcnt lgkmcnt(8)
	v_mfma_f32_16x16x32_bf16 v[50:53], v[188:191], v[98:101], v[50:53]
	s_waitcnt lgkmcnt(7)
	v_mfma_f32_16x16x32_bf16 v[78:81], v[128:131], v[94:97], v[78:81]
	s_waitcnt lgkmcnt(6)
	v_mfma_f32_16x16x32_bf16 v[74:77], v[132:135], v[94:97], v[74:77]
	s_waitcnt lgkmcnt(5)
	v_mfma_f32_16x16x32_bf16 v[70:73], v[136:139], v[94:97], v[70:73]
	s_waitcnt lgkmcnt(4)
	v_mfma_f32_16x16x32_bf16 v[66:69], v[140:143], v[94:97], v[66:69]
	s_waitcnt lgkmcnt(3)
	v_mfma_f32_16x16x32_bf16 v[62:65], v[144:147], v[94:97], v[62:65]
	s_waitcnt lgkmcnt(2)
	v_mfma_f32_16x16x32_bf16 v[58:61], v[148:151], v[94:97], v[58:61]
	s_waitcnt lgkmcnt(1)
	v_mfma_f32_16x16x32_bf16 v[54:57], v[152:155], v[94:97], v[54:57]
	s_waitcnt lgkmcnt(0)
	v_mfma_f32_16x16x32_bf16 v[50:53], v[156:159], v[94:97], v[50:53]
	s_setprio 0
